# retention unit decode remapped: forward and backward chains of one (batch, head) now run on the same XCD (h = u&7, dir = bit 5) so they share K/Q/V rows in L2
# baseline (speedup 1.0000x reference)
.LBB0_113:
	s_lshr_b32 s6, s40, 2
	s_and_b32 s0, s6, 0x1fffffc0
	s_sub_i32 s7, s0, 64
	s_cmpk_lt_i32 s40, 0x100
	s_cselect_b64 s[0:1], -1, 0
	s_and_b64 s[0:1], s[0:1], exec
	s_cselect_b32 s0, 0, s7
	s_and_b32 s1, s6, 56
	s_or_b32 s41, s0, s1
	s_ashr_i32 s0, s41, 4
	s_lshl_b32 s1, s0, 10
	s_add_i32 s8, s1, 0x1000
	s_lshl_b32 s9, s0, 8
	s_cmpk_lt_i32 s40, 0x100
	s_cselect_b64 s[6:7], -1, 0
	s_and_b64 s[0:1], s[6:7], exec
	s_cselect_b32 s45, 8, 2
	s_cselect_b32 s48, s8, s9
	s_cmpk_gt_i32 s40, 0xff
	s_cselect_b64 s[8:9], -1, 0
	s_and_b32 s0, s40, 6
	s_or_b32 s0, s41, s0
	s_bfe_u32 s1, s40, 0x10005
	s_bfe_i32 s12, s40, 0x10005
	s_and_b32 s44, s40, 7
	s_cmp_eq_u32 s1, 0
	s_cselect_b64 s[0:1], -1, 0
	v_readlane_b32 s80, v252, 40
	s_and_b64 s[10:11], s[0:1], exec
	v_readlane_b32 s88, v252, 48
	v_readlane_b32 s89, v252, 49
	v_readlane_b32 s90, v252, 50
	v_readlane_b32 s91, v252, 51
	s_cselect_b32 s13, s89, s91
	s_cselect_b32 s14, s88, s90
	s_or_b32 s10, s44, s36
	s_ashr_i32 s11, s10, 31
	s_lshl_b64 s[10:11], s[10:11], 2
	s_add_u32 s10, s14, s10
	s_addc_u32 s11, s13, s11
	s_add_i32 s49, s45, -1
	global_load_dword v104, v145, s[10:11]
	s_lshl_b32 s10, s49, 7
	s_waitcnt vmcnt(1)
	v_sub_u32_e32 v0, 0x7f, v149
	s_and_b32 s10, s12, s10
	v_cndmask_b32_e64 v236, v0, v149, s[0:1]
	s_add_i32 s14, s48, s10
	v_add_u32_e32 v0, s14, v236
	v_mov_b64_e32 v[16:17], s[42:43]
	v_sub_u32_e32 v2, 0x7f, v191
	v_mad_i64_i32 v[0:1], s[10:11], v0, s69, v[16:17]
	s_lshl_b32 s46, s44, 9
	v_cndmask_b32_e64 v237, v2, v191, s[0:1]
	v_lshl_add_u64 v[0:1], v[0:1], 0, s[46:47]
	v_add_u32_e32 v2, s14, v237
	v_sub_u32_e32 v8, 0x7f, v192
	v_lshl_add_u64 v[0:1], v[0:1], 0, v[144:145]
	v_mad_i64_i32 v[2:3], s[10:11], v2, s69, v[16:17]
	v_cndmask_b32_e64 v238, v8, v192, s[0:1]
	v_add_co_u32_e32 v0, vcc, s68, v0
	v_lshl_add_u64 v[2:3], v[2:3], 0, s[46:47]
	v_add_u32_e32 v8, s14, v238
	v_addc_co_u32_e32 v1, vcc, 0, v1, vcc
	v_lshl_add_u64 v[2:3], v[2:3], 0, v[144:145]
	v_mad_i64_i32 v[8:9], s[10:11], v8, s69, v[16:17]
	v_cndmask_b32_e64 v239, v194, v193, s[0:1]
	v_add_co_u32_e32 v4, vcc, s68, v2
	v_lshl_add_u64 v[8:9], v[8:9], 0, s[46:47]
	v_add_u32_e32 v10, s14, v239
	v_addc_co_u32_e32 v5, vcc, 0, v3, vcc
	v_lshl_add_u64 v[8:9], v[8:9], 0, v[144:145]
	v_mad_i64_i32 v[10:11], s[10:11], v10, s69, v[16:17]
	v_cndmask_b32_e64 v240, v196, v195, s[0:1]
	v_add_co_u32_e32 v8, vcc, s68, v8
	v_lshl_add_u64 v[10:11], v[10:11], 0, s[46:47]
	v_add_u32_e32 v18, s14, v240
	v_addc_co_u32_e32 v9, vcc, 0, v9, vcc
	v_lshl_add_u64 v[10:11], v[10:11], 0, v[144:145]
	v_mad_i64_i32 v[18:19], s[10:11], v18, s69, v[16:17]
	v_cndmask_b32_e64 v241, v198, v197, s[0:1]
	v_add_co_u32_e32 v12, vcc, s68, v10
	v_lshl_add_u64 v[18:19], v[18:19], 0, s[46:47]
	v_add_u32_e32 v20, s14, v241
	v_addc_co_u32_e32 v13, vcc, 0, v11, vcc
	v_lshl_add_u64 v[18:19], v[18:19], 0, v[144:145]
	v_mad_i64_i32 v[20:21], s[10:11], v20, s69, v[16:17]
	v_add_co_u32_e32 v18, vcc, s68, v18
	v_lshl_add_u64 v[20:21], v[20:21], 0, s[46:47]
	s_nop 0
	v_addc_co_u32_e32 v19, vcc, 0, v19, vcc
	v_lshl_add_u64 v[20:21], v[20:21], 0, v[144:145]
	v_add_co_u32_e32 v20, vcc, s68, v20
	v_cndmask_b32_e64 v242, v200, v199, s[0:1]
	global_load_dwordx4 v[0:3], v[0:1], off
	s_nop 0
	global_load_dwordx4 v[4:7], v[4:5], off
	s_nop 0
	global_load_dwordx4 v[8:11], v[8:9], off
	s_nop 0
	global_load_dwordx4 v[12:15], v[12:13], off
	v_addc_co_u32_e32 v21, vcc, 0, v21, vcc
	global_load_dwordx4 v[28:31], v[18:19], off
	global_load_dwordx4 v[44:47], v[20:21], off
	v_add_u32_e32 v18, s14, v242
	v_mad_i64_i32 v[18:19], s[10:11], v18, s69, v[16:17]
	v_cndmask_b32_e64 v243, v202, v201, s[0:1]
	v_lshl_add_u64 v[18:19], v[18:19], 0, s[46:47]
	v_add_u32_e32 v20, s14, v243
	v_lshl_add_u64 v[18:19], v[18:19], 0, v[144:145]
	v_mad_i64_i32 v[20:21], s[10:11], v20, s69, v[16:17]
	v_add_co_u32_e32 v18, vcc, s68, v18
	v_lshl_add_u64 v[20:21], v[20:21], 0, s[46:47]
	s_nop 0
	v_addc_co_u32_e32 v19, vcc, 0, v19, vcc
	v_lshl_add_u64 v[20:21], v[20:21], 0, v[144:145]
	v_add_co_u32_e32 v20, vcc, s68, v20
	v_cndmask_b32_e64 v244, v204, v203, s[0:1]
	s_nop 0
	v_addc_co_u32_e32 v21, vcc, 0, v21, vcc
	global_load_dwordx4 v[56:59], v[18:19], off
	global_load_dwordx4 v[60:63], v[20:21], off
	s_lshl_b32 s10, s40, 3
	v_add_u32_e32 v18, s14, v244
	s_and_b32 s50, s10, 0xc0
	v_mad_i64_i32 v[18:19], s[10:11], v18, s69, v[16:17]
	v_cndmask_b32_e64 v245, v206, v205, s[0:1]
	v_lshl_add_u64 v[18:19], v[18:19], 0, s[46:47]
	s_lshl_b32 s10, s50, 1
	s_mov_b32 s11, s47
	v_add_u32_e32 v20, s14, v245
	v_lshl_add_u64 v[18:19], v[18:19], 0, s[10:11]
	v_mov_b32_e32 v157, v145
	v_mad_i64_i32 v[20:21], s[12:13], v20, s69, v[16:17]
	v_lshl_add_u64 v[18:19], v[18:19], 0, v[156:157]
	s_movk_i32 s15, 0x2000
	v_lshl_add_u64 v[20:21], v[20:21], 0, s[46:47]
	v_add_co_u32_e32 v18, vcc, s15, v18
	v_lshl_add_u64 v[20:21], v[20:21], 0, s[10:11]
	s_nop 0
	v_addc_co_u32_e32 v19, vcc, 0, v19, vcc
	v_lshl_add_u64 v[20:21], v[20:21], 0, v[156:157]
	v_add_co_u32_e32 v20, vcc, s15, v20
	v_mov_b32_e32 v155, v145
	s_nop 0
	v_addc_co_u32_e32 v21, vcc, 0, v21, vcc
	global_load_dwordx4 v[64:67], v[18:19], off nt
	global_load_dwordx4 v[68:71], v[20:21], off nt
	v_sub_u32_e32 v18, 0x7f, v188
	v_cndmask_b32_e64 v105, v18, v188, s[0:1]
	v_add_u32_e32 v18, s14, v105
	v_mad_i64_i32 v[16:17], s[12:13], v18, s69, v[16:17]
	v_lshl_add_u64 v[16:17], v[16:17], 0, s[46:47]
	v_lshl_add_u64 v[52:53], v[16:17], 0, v[154:155]
	global_load_dwordx4 v[16:19], v[52:53], off
	global_load_dwordx4 v[20:23], v[52:53], off offset:64
	global_load_dwordx4 v[24:27], v[52:53], off offset:128
	global_load_dwordx4 v[32:35], v[52:53], off offset:192
	global_load_dwordx4 v[36:39], v[52:53], off offset:256
	global_load_dwordx4 v[40:43], v[52:53], off offset:320
	global_load_dwordx4 v[48:51], v[52:53], off offset:384
	s_nop 0
	global_load_dwordx4 v[52:55], v[52:53], off offset:448
	s_and_b64 vcc, exec, s[8:9]
	v_lshlrev_b32_e32 v158, 2, v146
	v_readlane_b32 s81, v252, 41
	v_readlane_b32 s82, v252, 42
	v_readlane_b32 s83, v252, 43
	v_readlane_b32 s84, v252, 44
	v_readlane_b32 s85, v252, 45
	v_readlane_b32 s86, v252, 46
	v_readlane_b32 s87, v252, 47
	v_readlane_b32 s92, v252, 52
	v_readlane_b32 s93, v252, 53
	v_readlane_b32 s94, v252, 54
	v_readlane_b32 s95, v252, 55
	s_cbranch_vccnz .LBB0_115
	v_readlane_b32 s80, v253, 0
	s_and_b64 s[12:13], s[0:1], exec
	v_readlane_b32 s81, v253, 1
	s_cselect_b32 s11, s31, s81
	s_cselect_b32 s14, s30, s80
	s_and_b32 s12, s41, -16
	s_add_i32 s12, s12, s36
	s_or_b32 s12, s44, s12
	s_ashr_i32 s13, s12, 31
	s_lshl_b64 s[12:13], s[12:13], 18
	s_add_u32 s12, s14, s12
	s_addc_u32 s11, s11, s13
	s_lshl_b32 s13, s50, 2
	s_add_u32 s12, s12, s13
	s_addc_u32 s13, s11, 0
	v_mov_b32_e32 v159, v145
	v_lshl_add_u64 v[72:73], s[12:13], 0, v[158:159]
	v_lshl_add_u64 v[72:73], v[152:153], 2, v[72:73]
	global_load_dwordx4 v[100:103], v[72:73], off nt
	global_load_dwordx4 v[96:99], v[72:73], off offset:64 nt
	global_load_dwordx4 v[92:95], v[72:73], off offset:128 nt
	global_load_dwordx4 v[88:91], v[72:73], off offset:192 nt
	v_add_co_u32_e32 v72, vcc, 0x4000, v72
	v_readlane_b32 s82, v253, 2
	s_nop 0
	v_addc_co_u32_e32 v73, vcc, 0, v73, vcc
	global_load_dwordx4 v[84:87], v[72:73], off nt
	global_load_dwordx4 v[80:83], v[72:73], off offset:64 nt
	global_load_dwordx4 v[76:79], v[72:73], off offset:128 nt
	s_nop 0
	global_load_dwordx4 v[72:75], v[72:73], off offset:192 nt
	v_readlane_b32 s83, v253, 3
	v_readlane_b32 s84, v253, 4
	v_readlane_b32 s85, v253, 5
	v_readlane_b32 s86, v253, 6
	v_readlane_b32 s87, v253, 7
	v_readlane_b32 s88, v253, 8
	v_readlane_b32 s89, v253, 9
	v_readlane_b32 s90, v253, 10
	v_readlane_b32 s91, v253, 11
	v_readlane_b32 s92, v253, 12
	v_readlane_b32 s93, v253, 13
	v_readlane_b32 s94, v253, 14
	v_readlane_b32 s95, v253, 15
	s_branch .LBB0_116
